# v111 + prologue (weight transposes / rmsnorm rows): work items interleaved across workgroups (index = wave*grid + block) so the 7th transpose tile falls on one wave per workgroup instead of all waves
# speedup vs baseline: 1.0035x; 1.0035x over previous
.LBB0_43:
	s_or_b64 exec, exec, s[28:29]
	s_lshr_b32 s55, s81, 6
	s_lshl_b32 s79, s2, 3
	s_mul_i32 s6, s55, s24
	s_add_i32 s6, s6, s2
	s_add_u32 s46, s22, 0x200000
	s_addc_u32 s47, s23, 0
	s_add_u32 s34, s22, 0x2200000
	s_addc_u32 s35, s23, 0
	s_add_u32 s28, s22, 0x2a00000
	s_addc_u32 s29, s23, 0
	s_add_u32 s30, s22, 0x3200000
	s_addc_u32 s31, s23, 0
	s_cmpk_lt_i32 s6, 0x3100
	s_cselect_b64 s[50:51], -1, 0
	v_and_b32_e32 v64, 63, v225
	s_and_b64 vcc, exec, s[50:51]
	s_cbranch_vccz .LBB0_48
	s_mov_b32 s67, 1
	s_cmpk_lt_i32 s6, 0x2000
	s_movk_i32 s72, 0x2000
	s_cbranch_scc1 .LBB0_50
	s_cmpk_gt_u32 s6, 0x27ff
	s_cbranch_scc0 .LBB0_51
	s_cmpk_gt_u32 s6, 0x2fff
	s_cbranch_scc0 .LBB0_52
	s_add_i32 s66, s6, 0xffffd000
	s_mov_b64 s[4:5], 0
	s_mov_b64 s[56:57], s[16:17]
	s_movk_i32 s7, 0x100
	s_mov_b64 s[48:49], s[30:31]
	s_cbranch_execz .LBB0_53
	s_branch .LBB0_54
